# LRU summary: next unit's x rows requested (L2 warm-up) while the current unit computes
# speedup vs baseline: 1.0036x; 1.0036x over previous
.LBB0_672:
	s_or_b64 exec, exec, s[40:41]
	v_cndmask_b32_e64 v158, 0, 1.0, s[16:17]
	v_cndmask_b32_e64 v194, 0, 1.0, s[18:19]
	s_waitcnt vmcnt(23)
	v_lshlrev_b32_e32 v198, 16, v6
	v_and_b32_e32 v199, 0xffff0000, v6
	v_lshlrev_b32_e32 v6, 16, v7
	v_and_b32_e32 v7, 0xffff0000, v7
	s_waitcnt vmcnt(20)
	v_pk_mul_f32 v[128:129], v[158:159], v[128:129] op_sel_hi:[0,1]
	v_cndmask_b32_e64 v196, 0, 1.0, s[20:21]
	v_pk_mul_f32 v[126:127], v[158:159], v[126:127] op_sel_hi:[0,1]
	s_waitcnt vmcnt(17)
	v_lshlrev_b32_e32 v200, 16, v10
	v_and_b32_e32 v201, 0xffff0000, v10
	v_lshlrev_b32_e32 v10, 16, v11
	v_and_b32_e32 v11, 0xffff0000, v11
	s_waitcnt vmcnt(13)
	v_pk_mul_f32 v[132:133], v[194:195], v[132:133] op_sel_hi:[0,1]
	s_waitcnt vmcnt(0)
	v_add_u32_e32 v206, v252, v253
	v_mov_b32_e32 v207, 0x22048
	v_cmp_eq_u32_e64 s[50:51], 0, v0
	s_and_saveexec_b64 s[48:49], s[50:51]
	ds_write_b32 v207, v206
	s_or_b64 exec, exec, s[48:49]
	v_pk_fma_f32 v[6:7], v[128:129], v[6:7], v[144:145]
	v_pk_mul_f32 v[130:131], v[194:195], v[130:131] op_sel_hi:[0,1]
	v_lshlrev_b32_e32 v202, 16, v50
	v_and_b32_e32 v203, 0xffff0000, v50
	v_lshlrev_b32_e32 v50, 16, v51
	v_and_b32_e32 v51, 0xffff0000, v51
	v_pk_mul_f32 v[136:137], v[196:197], v[136:137] op_sel_hi:[0,1]
	v_pk_fma_f32 v[126:127], v[126:127], v[198:199], v[142:143]
	v_pk_fma_f32 v[6:7], v[132:133], v[10:11], v[6:7]
	v_pk_mul_f32 v[134:135], v[196:197], v[134:135] op_sel_hi:[0,1]
	v_lshlrev_b32_e32 v204, 16, v58
	v_and_b32_e32 v205, 0xffff0000, v58
	v_lshlrev_b32_e32 v58, 16, v59
	v_and_b32_e32 v59, 0xffff0000, v59
	v_pk_mul_f32 v[140:141], v[152:153], v[140:141]
	v_pk_fma_f32 v[10:11], v[130:131], v[200:201], v[126:127]
	v_pk_fma_f32 v[6:7], v[136:137], v[50:51], v[6:7]
	v_pk_mul_f32 v[138:139], v[150:151], v[138:139]
	v_pk_fma_f32 v[10:11], v[134:135], v[202:203], v[10:11]
	v_pk_fma_f32 v[128:129], v[140:141], v[58:59], v[6:7]
	v_lshlrev_b32_e32 v6, 16, v68
	v_and_b32_e32 v7, 0xffff0000, v68
	v_pk_mul_f32 v[58:59], v[158:159], v[106:107] op_sel_hi:[0,1]
	v_pk_fma_f32 v[126:127], v[138:139], v[204:205], v[10:11]
	v_lshlrev_b32_e32 v10, 16, v69
	v_and_b32_e32 v11, 0xffff0000, v69
	v_pk_mul_f32 v[50:51], v[158:159], v[108:109] op_sel_hi:[0,1]
	v_lshlrev_b32_e32 v68, 16, v76
	v_and_b32_e32 v69, 0xffff0000, v76
	v_pk_mul_f32 v[106:107], v[194:195], v[110:111] op_sel_hi:[0,1]
	v_pk_fma_f32 v[6:7], v[58:59], v[6:7], v[118:119]
	v_lshlrev_b32_e32 v76, 16, v77
	v_and_b32_e32 v77, 0xffff0000, v77
	v_pk_mul_f32 v[108:109], v[194:195], v[112:113] op_sel_hi:[0,1]
	v_lshlrev_b32_e32 v110, 16, v88
	v_and_b32_e32 v111, 0xffff0000, v88
	v_pk_mul_f32 v[114:115], v[196:197], v[114:115] op_sel_hi:[0,1]
	v_pk_fma_f32 v[10:11], v[50:51], v[10:11], v[120:121]
	v_pk_fma_f32 v[6:7], v[106:107], v[68:69], v[6:7]
	v_lshlrev_b32_e32 v88, 16, v89
	v_and_b32_e32 v89, 0xffff0000, v89
	v_pk_mul_f32 v[112:113], v[196:197], v[116:117] op_sel_hi:[0,1]
	v_lshlrev_b32_e32 v116, 16, v96
	v_and_b32_e32 v117, 0xffff0000, v96
	v_pk_mul_f32 v[122:123], v[150:151], v[122:123]
	v_pk_fma_f32 v[10:11], v[108:109], v[76:77], v[10:11]
	v_pk_fma_f32 v[6:7], v[114:115], v[110:111], v[6:7]
	v_lshlrev_b32_e32 v96, 16, v97
	v_and_b32_e32 v97, 0xffff0000, v97
	v_pk_mul_f32 v[124:125], v[152:153], v[124:125]
	v_pk_fma_f32 v[10:11], v[112:113], v[88:89], v[10:11]
	v_pk_fma_f32 v[106:107], v[122:123], v[116:117], v[6:7]
	v_lshlrev_b32_e32 v6, 16, v66
	v_and_b32_e32 v7, 0xffff0000, v66
	v_pk_mul_f32 v[58:59], v[158:159], v[70:71] op_sel_hi:[0,1]
	v_pk_fma_f32 v[108:109], v[124:125], v[96:97], v[10:11]
	v_lshlrev_b32_e32 v10, 16, v67
	v_and_b32_e32 v11, 0xffff0000, v67
	v_pk_mul_f32 v[50:51], v[158:159], v[72:73] op_sel_hi:[0,1]
	v_lshlrev_b32_e32 v66, 16, v74
	v_and_b32_e32 v67, 0xffff0000, v74
	v_pk_mul_f32 v[72:73], v[194:195], v[78:79] op_sel_hi:[0,1]
	v_pk_fma_f32 v[6:7], v[58:59], v[6:7], v[98:99]
	v_lshlrev_b32_e32 v68, 16, v75
	v_and_b32_e32 v69, 0xffff0000, v75
	v_pk_mul_f32 v[70:71], v[194:195], v[80:81] op_sel_hi:[0,1]
	v_lshlrev_b32_e32 v74, 16, v86
	v_and_b32_e32 v75, 0xffff0000, v86
	v_pk_mul_f32 v[80:81], v[196:197], v[90:91] op_sel_hi:[0,1]
	v_pk_fma_f32 v[10:11], v[50:51], v[10:11], v[100:101]
	v_pk_fma_f32 v[6:7], v[72:73], v[66:67], v[6:7]
	v_lshlrev_b32_e32 v76, 16, v87
	v_and_b32_e32 v77, 0xffff0000, v87
	v_pk_mul_f32 v[78:79], v[196:197], v[92:93] op_sel_hi:[0,1]
	v_lshlrev_b32_e32 v86, 16, v94
	v_and_b32_e32 v87, 0xffff0000, v94
	v_pk_mul_f32 v[92:93], v[150:151], v[102:103]
	v_pk_fma_f32 v[10:11], v[70:71], v[68:69], v[10:11]
	v_pk_fma_f32 v[6:7], v[80:81], v[74:75], v[6:7]
	v_lshlrev_b32_e32 v88, 16, v95
	v_and_b32_e32 v89, 0xffff0000, v95
	v_pk_mul_f32 v[90:91], v[152:153], v[104:105]
	v_pk_fma_f32 v[10:11], v[78:79], v[76:77], v[10:11]
	v_pk_fma_f32 v[66:67], v[92:93], v[86:87], v[6:7]
	v_lshlrev_b32_e32 v6, 16, v8
	v_and_b32_e32 v7, 0xffff0000, v8
	v_lshlrev_b32_e32 v8, 16, v9
	v_and_b32_e32 v9, 0xffff0000, v9
	v_pk_mul_f32 v[4:5], v[158:159], v[4:5] op_sel_hi:[0,1]
	v_pk_mul_f32 v[2:3], v[158:159], v[2:3] op_sel_hi:[0,1]
	v_pk_fma_f32 v[68:69], v[90:91], v[88:89], v[10:11]
	v_lshlrev_b32_e32 v10, 16, v12
	v_and_b32_e32 v11, 0xffff0000, v12
	v_lshlrev_b32_e32 v12, 16, v13
	v_and_b32_e32 v13, 0xffff0000, v13
	v_pk_mul_f32 v[22:23], v[194:195], v[22:23] op_sel_hi:[0,1]
	v_pk_mul_f32 v[24:25], v[194:195], v[24:25] op_sel_hi:[0,1]
	v_pk_fma_f32 v[2:3], v[2:3], v[6:7], v[82:83]
	v_pk_fma_f32 v[4:5], v[4:5], v[8:9], v[84:85]
	v_lshlrev_b32_e32 v50, 16, v52
	v_and_b32_e32 v51, 0xffff0000, v52
	v_lshlrev_b32_e32 v52, 16, v53
	v_and_b32_e32 v53, 0xffff0000, v53
	v_pk_mul_f32 v[56:57], v[196:197], v[56:57] op_sel_hi:[0,1]
	v_pk_mul_f32 v[54:55], v[196:197], v[54:55] op_sel_hi:[0,1]
	v_pk_fma_f32 v[4:5], v[24:25], v[12:13], v[4:5]
	v_pk_fma_f32 v[2:3], v[22:23], v[10:11], v[2:3]
	v_lshlrev_b32_e32 v58, 16, v60
	v_and_b32_e32 v59, 0xffff0000, v60
	v_lshlrev_b32_e32 v60, 16, v61
	v_and_b32_e32 v61, 0xffff0000, v61
	v_pk_mul_f32 v[64:65], v[152:153], v[64:65]
	v_pk_mul_f32 v[62:63], v[150:151], v[62:63]
	v_pk_fma_f32 v[2:3], v[54:55], v[50:51], v[2:3]
	v_pk_fma_f32 v[4:5], v[56:57], v[52:53], v[4:5]
	v_pk_fma_f32 v[2:3], v[62:63], v[58:59], v[2:3]
	v_pk_fma_f32 v[4:5], v[64:65], v[60:61], v[4:5]
	ds_write_b128 v167, v[66:69]
	ds_write_b128 v167, v[106:109] offset:16
	ds_write_b128 v167, v[126:129] offset:32
	ds_write_b128 v167, v[2:5] offset:48
	v_cvt_pk_bf16_f32 v6, v66, v67
	v_cvt_pk_bf16_f32 v7, v68, v69
	v_cvt_pk_bf16_f32 v8, v106, v107
	v_cvt_pk_bf16_f32 v9, v108, v109
	v_cvt_pk_bf16_f32 v10, v126, v127
	v_cvt_pk_bf16_f32 v11, v128, v129
	v_cvt_pk_bf16_f32 v12, v2, v3
	v_cvt_pk_bf16_f32 v13, v4, v5
	ds_write_b128 v168, v[6:9] offset:33792
	ds_write_b128 v168, v[10:13] offset:33808
	s_waitcnt lgkmcnt(0)
	s_barrier
	v_mov_b32_e32 v207, 0x22048
	ds_read_b32 v206, v207
	v_lshrrev_b32_e32 v208, 3, v0
	v_and_b32_e32 v209, 7, v0
	v_lshlrev_b32_e32 v209, 5, v209
	s_waitcnt lgkmcnt(0)
	v_readfirstlane_b32 s47, v206
	s_nop 0
	s_cmp_lt_u32 s47, 0x780
	s_cbranch_scc0 .Llpf_skip
	s_bfe_u32 s48, s47, 0x60004
	s_lshl_b32 s48, s48, 6
	s_lshr_b32 s49, s47, 10
	s_lshl_b32 s49, s49, 12
	s_or_b32 s48, s48, s49
	s_and_b32 s49, s47, 15
	s_lshl_b32 s49, s49, 8
	v_add_u32_e32 v208, s48, v208
	v_lshlrev_b32_e32 v208, 12, v208
	v_add3_u32 v208, v208, v209, s49
	global_load_dwordx4 v[212:215], v208, s[26:27]
	global_load_dwordx4 v[216:219], v208, s[26:27] offset:16
.Llpf_skip:
	ds_read_b128 v[2:5], v170 offset:33792
	ds_read_b128 v[6:9], v170 offset:33856
	s_waitcnt lgkmcnt(1)
	v_mfma_f32_16x16x32_bf16 v[10:13], v[2:5], v[34:37], 0
	s_mov_b32 s16, 0x3f2aaaab
	v_mfma_f32_16x16x32_bf16 v[2:5], v[2:5], v[46:49], 0
	s_waitcnt lgkmcnt(0)
	v_mfma_f32_16x16x32_bf16 v[10:13], v[6:9], v[38:41], v[10:13]
	v_mfma_f32_16x16x32_bf16 v[2:5], v[6:9], v[42:45], v[2:5]
	ds_read_b128 v[6:9], v170 offset:33920
	ds_read_b128 v[22:25], v170 offset:33984
	s_waitcnt lgkmcnt(1)
	v_mfma_f32_16x16x32_bf16 v[10:13], v[6:9], v[26:29], v[10:13]
	v_mfma_f32_16x16x32_bf16 v[2:5], v[6:9], v[30:33], v[2:5]
	s_waitcnt lgkmcnt(0)
	v_mfma_f32_16x16x32_bf16 v[54:57], v[22:25], v[14:17], v[10:13]
	ds_read_b128 v[6:9], v170 offset:38144
	s_nop 3
	ds_read_b128 v[10:13], v170 offset:38208
	v_mfma_f32_16x16x32_bf16 v[2:5], v[22:25], v[18:21], v[2:5]
	s_waitcnt lgkmcnt(1)
	v_mfma_f32_16x16x32_bf16 v[22:25], v[6:9], v[34:37], 0
	v_mfma_f32_16x16x32_bf16 v[6:9], v[6:9], v[46:49], 0
	s_waitcnt lgkmcnt(0)
	v_mfma_f32_16x16x32_bf16 v[22:25], v[10:13], v[38:41], v[22:25]
	v_mfma_f32_16x16x32_bf16 v[6:9], v[10:13], v[42:45], v[6:9]
	ds_read_b128 v[10:13], v170 offset:38272
	ds_read_b128 v[58:61], v170 offset:38336
	s_waitcnt lgkmcnt(1)
	v_mfma_f32_16x16x32_bf16 v[22:25], v[10:13], v[26:29], v[22:25]
	v_mfma_f32_16x16x32_bf16 v[6:9], v[10:13], v[30:33], v[6:9]
	s_waitcnt lgkmcnt(0)
	v_mfma_f32_16x16x32_bf16 v[50:53], v[58:61], v[14:17], v[22:25]
	ds_read_b128 v[10:13], v170 offset:42496
	s_nop 3
	ds_read_b128 v[22:25], v170 offset:42560
	v_mfma_f32_16x16x32_bf16 v[6:9], v[58:61], v[18:21], v[6:9]
	s_waitcnt lgkmcnt(1)
	v_mfma_f32_16x16x32_bf16 v[58:61], v[10:13], v[34:37], 0
	v_mfma_f32_16x16x32_bf16 v[10:13], v[10:13], v[46:49], 0
	s_waitcnt lgkmcnt(0)
	v_mfma_f32_16x16x32_bf16 v[58:61], v[22:25], v[38:41], v[58:61]
	v_mfma_f32_16x16x32_bf16 v[10:13], v[22:25], v[42:45], v[10:13]
	ds_read_b128 v[22:25], v170 offset:42624
	ds_read_b128 v[62:65], v170 offset:42688
	s_waitcnt lgkmcnt(1)
	v_mfma_f32_16x16x32_bf16 v[58:61], v[22:25], v[26:29], v[58:61]
	v_mfma_f32_16x16x32_bf16 v[10:13], v[22:25], v[30:33], v[10:13]
	s_waitcnt lgkmcnt(0)
	v_mfma_f32_16x16x32_bf16 v[22:25], v[62:65], v[14:17], v[58:61]
	v_mfma_f32_16x16x32_bf16 v[10:13], v[62:65], v[18:21], v[10:13]
	s_nop 3
	ds_read_b128 v[58:61], v171 offset:33792
	ds_read_b128 v[62:65], v171 offset:33856
	s_waitcnt lgkmcnt(1)
	v_mfma_f32_16x16x32_bf16 v[34:37], v[58:61], v[34:37], 0
	v_mfma_f32_16x16x32_bf16 v[46:49], v[58:61], v[46:49], 0
	s_waitcnt lgkmcnt(0)
	v_mfma_f32_16x16x32_bf16 v[34:37], v[62:65], v[38:41], v[34:37]
	v_mfma_f32_16x16x32_bf16 v[38:41], v[62:65], v[42:45], v[46:49]
	ds_read_b128 v[42:45], v171 offset:33920
	s_nop 3
	ds_read_b128 v[46:49], v171 offset:33984
	s_waitcnt lgkmcnt(1)
	v_mfma_f32_16x16x32_bf16 v[26:29], v[42:45], v[26:29], v[34:37]
	s_nop 2
	v_mul_f32_e32 v34, 0xbfb8aa3b, v157
	v_mfma_f32_16x16x32_bf16 v[30:33], v[42:45], v[30:33], v[38:41]
	v_exp_f32_e32 v44, v34
	s_waitcnt lgkmcnt(0)
	v_mfma_f32_16x16x32_bf16 v[14:17], v[46:49], v[14:17], v[26:29]
	s_nop 2
	v_add_f32_e32 v28, 1.0, v44
	v_add_f32_e32 v26, -1.0, v28
	v_sub_f32_e32 v27, v26, v28
	v_add_f32_e32 v27, 1.0, v27
	v_sub_f32_e32 v26, v44, v26
	v_add_f32_e32 v29, v26, v27
	v_frexp_mant_f32_e32 v34, v28
	v_cvt_f64_f32_e32 v[26:27], v28
	v_frexp_exp_i32_f64_e32 v26, v[26:27]
	v_cmp_gt_f32_e32 vcc, s16, v34
	v_mfma_f32_16x16x32_bf16 v[18:21], v[46:49], v[18:21], v[30:33]
	s_nop 0
	v_subbrev_co_u32_e32 v38, vcc, 0, v26, vcc
	v_sub_u32_e32 v26, 0, v38
	v_ldexp_f32 v27, v28, v26
	v_add_f32_e32 v28, -1.0, v27
	v_add_f32_e32 v34, 1.0, v27
	v_ldexp_f32 v26, v29, v26
	v_add_f32_e32 v29, 1.0, v28
	v_add_f32_e32 v35, -1.0, v34
	v_sub_f32_e32 v29, v27, v29
	v_sub_f32_e32 v27, v27, v35
	v_add_f32_e32 v29, v26, v29
	v_add_f32_e32 v26, v26, v27
	v_add_f32_e32 v39, v34, v26
	v_rcp_f32_e32 v41, v39
	v_sub_f32_e32 v27, v39, v34
	v_sub_f32_e32 v40, v26, v27
	v_add_f32_e32 v27, v28, v29
	v_mul_f32_e32 v43, v27, v41
	v_sub_f32_e32 v26, v27, v28
	v_mul_f32_e32 v28, v39, v43
	v_fma_f32 v34, v43, v39, -v28
	v_fmac_f32_e32 v34, v43, v40
	v_sub_f32_e32 v42, v29, v26
	v_add_f32_e32 v26, v28, v34
	v_sub_f32_e32 v29, v27, v26
	v_pk_add_f32 v[36:37], v[26:27], v[28:29] neg_lo:[0,1] neg_hi:[0,1]
	v_mov_b32_e32 v35, v26
	v_pk_add_f32 v[26:27], v[36:37], v[34:35] neg_lo:[0,1] neg_hi:[0,1]
	v_cmp_neq_f32_e32 vcc, s44, v44
	v_add_f32_e32 v27, v42, v27
	v_add_f32_e32 v26, v26, v27
	v_add_f32_e32 v27, v29, v26
	v_mul_f32_e32 v42, v41, v27
	v_mul_f32_e32 v28, v39, v42
	v_fma_f32 v34, v42, v39, -v28
	v_fmac_f32_e32 v34, v42, v40
	v_sub_f32_e32 v29, v29, v27
	v_add_f32_e32 v39, v26, v29
	v_add_f32_e32 v26, v28, v34
	v_sub_f32_e32 v29, v27, v26
	v_pk_add_f32 v[36:37], v[26:27], v[28:29] neg_lo:[0,1] neg_hi:[0,1]
	v_mov_b32_e32 v35, v26
	v_pk_add_f32 v[26:27], v[36:37], v[34:35] neg_lo:[0,1] neg_hi:[0,1]
	s_nop 0
	v_add_f32_e32 v27, v39, v27
	v_add_f32_e32 v26, v26, v27
	v_add_f32_e32 v27, v43, v42
	v_add_f32_e32 v26, v29, v26
	v_sub_f32_e32 v28, v27, v43
	v_mul_f32_e32 v26, v41, v26
	v_sub_f32_e32 v28, v42, v28
	v_add_f32_e32 v28, v28, v26
	v_add_f32_e32 v34, v27, v28
	v_mul_f32_e32 v35, v34, v34
	v_fmamk_f32 v26, v35, 0x3e9b6dac, v185
	v_fmaak_f32 v157, v35, v26, 0x3f2aaada
	v_cvt_f32_i32_e32 v26, v38
	v_sub_f32_e32 v27, v34, v27
	v_sub_f32_e32 v27, v28, v27
	v_ldexp_f32 v36, v27, 1
	v_mul_f32_e32 v27, v34, v35
	v_ldexp_f32 v29, v34, 1
	v_pk_mul_f32 v[34:35], v[26:27], v[156:157]
	s_nop 0
	v_fma_f32 v28, v26, s43, -v34
	v_fmac_f32_e32 v28, 0xb102e308, v26
	v_pk_add_f32 v[26:27], v[34:35], v[28:29]
	s_nop 0
	v_sub_f32_e32 v29, v27, v29
	v_sub_f32_e32 v29, v35, v29
	v_add_f32_e32 v37, v36, v29
	v_mov_b32_e32 v36, v34
	v_pk_add_f32 v[34:35], v[26:27], v[34:35] neg_lo:[0,1] neg_hi:[0,1]
	v_pk_add_f32 v[38:39], v[26:27], v[36:37]
	v_mov_b32_e32 v29, v26
	v_mov_b32_e32 v35, v39
	v_pk_add_f32 v[40:41], v[28:29], v[34:35] neg_lo:[0,1] neg_hi:[0,1]
	v_pk_add_f32 v[28:29], v[28:29], v[34:35]
	v_mov_b32_e32 v36, v37
	v_pk_add_f32 v[34:35], v[28:29], v[26:27] op_sel:[1,0] op_sel_hi:[0,1] neg_lo:[0,1] neg_hi:[0,1]
	v_pk_add_f32 v[42:43], v[38:39], v[34:35] op_sel_hi:[1,0] neg_lo:[0,1] neg_hi:[0,1]
	v_mov_b32_e32 v38, v39
	v_mov_b32_e32 v39, v29
	v_pk_mov_b32 v[34:35], v[26:27], v[34:35] op_sel:[1,0]
	v_mov_b32_e32 v37, v26
	v_pk_add_f32 v[34:35], v[38:39], v[34:35] neg_lo:[0,1] neg_hi:[0,1]
	v_mov_b32_e32 v42, v40
	v_pk_add_f32 v[26:27], v[36:37], v[34:35] neg_lo:[0,1] neg_hi:[0,1]
	v_mov_b32_e32 v41, v29
	v_pk_add_f32 v[34:35], v[42:43], v[26:27]
	s_nop 0
	v_pk_add_f32 v[36:37], v[34:35], v[34:35] op_sel:[0,1] op_sel_hi:[1,0]
	s_nop 0
	v_pk_add_f32 v[28:29], v[28:29], v[36:37] op_sel:[1,0] op_sel_hi:[0,1]
	v_mov_b32_e32 v35, v28
	v_pk_add_f32 v[38:39], v[34:35], v[40:41] neg_lo:[0,1] neg_hi:[0,1]
	v_mov_b32_e32 v27, v36
	v_sub_f32_e32 v29, v34, v38
	v_pk_add_f32 v[26:27], v[26:27], v[38:39] neg_lo:[0,1] neg_hi:[0,1]
	v_sub_f32_e32 v29, v40, v29
	v_add_f32_e32 v26, v26, v29
	v_add_f32_e32 v26, v26, v27
	v_add_f32_e32 v27, v192, v54
	v_mul_f32_e32 v27, 0xbfb8aa3b, v27
	v_exp_f32_e32 v27, v27
	v_add_f32_e32 v26, v28, v26
	v_cndmask_b32_e32 v26, v186, v26, vcc
	v_cmp_ngt_f32_e32 vcc, -1.0, v44
	v_add_f32_e32 v27, 1.0, v27
	v_rcp_f32_e32 v27, v27
	v_cndmask_b32_e32 v26, v187, v26, vcc
	v_cmp_neq_f32_e32 vcc, -1.0, v44
	s_nop 1
	v_cndmask_b32_e32 v26, v188, v26, vcc
	v_cmp_lt_f32_e64 vcc, |v44|, s45
	s_nop 1
	v_cndmask_b32_e32 v26, v26, v44, vcc
	v_mul_f32_e32 v37, 0xc1000000, v26
	v_mul_f32_e32 v26, v37, v27
	v_mul_f32_e32 v27, 0x3fb8aa3b, v26
	v_exp_f32_e32 v27, v27
	v_add_f32_e32 v26, v26, v26
	v_cmp_nlt_f32_e32 vcc, s46, v26
	s_and_saveexec_b64 s[16:17], vcc
	s_xor_b64 s[16:17], exec, s[16:17]
	v_fma_f32 v39, -v27, v27, 1.0
	s_andn2_saveexec_b64 s[16:17], s[16:17]
	s_cbranch_execz .LBB0_676
	v_pk_mul_f32 v[28:29], v[26:27], s[0:1] op_sel_hi:[0,1]
	v_add_f32_e32 v29, 1.0, v29
	v_mul_f32_e32 v33, 0x3e4ccccd, v26
	v_fma_f32 v28, v28, v29, 1.0
	v_mul_f32_e32 v32, 0x3e800000, v26
	v_fma_f32 v28, v33, v28, 1.0
	v_mul_f32_e32 v31, 0x3eaaaaab, v26
	v_fma_f32 v28, v32, v28, 1.0
	v_mul_f32_e32 v30, 0.5, v26
	v_fma_f32 v28, v31, v28, 1.0
	v_fma_f32 v28, v30, v28, 1.0
	v_mul_f32_e64 v39, v28, -v26
